# P7 hyena_gate: loop-top wait counted (vmcnt(4)) so it no longer waits for the previous tile's 4 stores; prologue path drains once; on top of v45
# speedup vs baseline: 1.0002x; 1.0002x over previous
; __device__ __forceinline__ void hyena_gate(const Args& a, LAS unsigned char* lds, int bid, int G, int tid) {
;     ...
;     if (bid < NT) { const int m0 = (bid / 12) * 256, c0 = (bid % 12) * 64, L = m0 < MP ? LP : LS; hy_load6(ZHY, c0 + 8 * cg, m0 + 4 * tq, L, n0);
;         const v4u* dp = (const v4u*)(UCT + (size_t)(c0 + yc) * MT + m0);
; #pragma unroll
;         for (int k = 0; k < 4; ++k) ny[k] = dp[8 * k + yp]; }
;     for (int it = bid; it < NT; it += G) {
;         const int m0 = (it / 12) * 256, c0 = (it % 12) * 64, mr0 = m0 + 4 * tq, ca = c0 + 8 * cg;
;         v4u z0[6];
; #pragma unroll
;         for (int i = 0; i < 6; ++i) z0[i] = n0[i];
.LBB0_945:
	s_or_b64 exec, exec, s[6:7]
	s_add_u32 s6, s4, 0x2a000000
	s_addc_u32 s7, s5, 0
	v_add_u32_e32 v4, s10, v3
	s_mov_b32 s15, 0x30000
	v_mov_b64_e32 v[0:1], s[6:7]
	v_mad_i64_i32 v[0:1], s[10:11], v4, s15, v[0:1]
	v_lshl_add_u64 v[0:1], s[8:9], 1, v[0:1]
	v_mov_b32_e32 v97, 0
	v_lshlrev_b32_e32 v96, 4, v2
	v_lshl_add_u64 v[0:1], v[0:1], 0, v[96:97]
	global_load_dwordx4 v[8:11], v[0:1], off offset:384
	global_load_dwordx4 v[12:15], v[0:1], off offset:256
	global_load_dwordx4 v[16:19], v[0:1], off offset:128
	global_load_dwordx4 v[20:23], v[0:1], off
	s_movk_i32 s8, 0x208
	s_add_u32 s4, s4, 0x33000000
	v_mul_lo_u32 v0, v3, s8
	s_addc_u32 s5, s5, 0
	v_add_u32_e32 v0, 0, v0
	v_lshlrev_b32_e32 v1, 9, v3
	s_lshl_b32 s8, s96, 8
	v_sub_u32_e32 v1, v0, v1
	v_mul_u32_u24_e32 v4, 0x1040, v2
	s_lshl_b32 s16, s70, 6
	s_add_i32 s8, s8, 0
	v_add_u32_e32 v101, s16, v3
	v_lshl_add_u32 v102, v2, 5, s8
	v_add_u32_e32 v103, v0, v96
	v_lshlrev_b32_e32 v96, 4, v2
	v_add_u32_e32 v104, v1, v4
	s_waitcnt vmcnt(4)
	v_mov_b64_e32 v[0:1], v[40:41]
	v_mov_b64_e32 v[32:33], v[44:45]
	v_mov_b64_e32 v[36:37], v[52:53]
	v_mov_b64_e32 v[24:25], v[60:61]
	v_mov_b64_e32 v[28:29], v[72:73]
	v_mov_b64_e32 v[4:5], v[48:49]
	v_or_b32_e32 v100, s16, v98
	s_lshl_b32 s17, s96, 6
	s_lshl_b32 s18, s70, 8
	s_movk_i32 s19, 0x1fff
	s_movk_i32 s20, 0x600
	s_mov_b32 s22, s96
	v_mov_b64_e32 v[2:3], v[42:43]
	v_mov_b64_e32 v[34:35], v[46:47]
	v_mov_b64_e32 v[38:39], v[54:55]
	v_mov_b64_e32 v[26:27], v[62:63]
	v_mov_b64_e32 v[30:31], v[74:75]
	v_mov_b64_e32 v[6:7], v[50:51]
	s_waitcnt vmcnt(0)
	s_branch .LBB0_948

; #define LAS __attribute__((address_space(3)))
; __device__ __forceinline__ void hyena_gate(const Args& a, LAS unsigned char* lds, int bid, int G, int tid) {
;     ...
;     for (int it = bid; it < NT; it += G) {
;         const int m0 = (it / 12) * 256, c0 = (it % 12) * 64, mr0 = m0 + 4 * tq, ca = c0 + 8 * cg;
;         v4u z0[6];
; #pragma unroll
;         for (int i = 0; i < 6; ++i) z0[i] = n0[i];
;         { LAS v2u* sp = (LAS v2u*)(tile + yc * HT_PITCH);
; #pragma unroll
;           for (int k = 0; k < 4; ++k) { const int ch = 8 * k + yp; const v4u o = ny[k]; v2u lo, hv; lo.x = o.x; lo.y = o.y; hv.x = o.z; hv.y = o.w; sp[2 * ch] = lo; sp[2 * ch + 1] = hv; } }
;         { const int itn = it + G; if (itn < NT) { const int m0n = (itn / 12) * 256, c0n = (itn % 12) * 64, Ln = m0n < MP ? LP : LS; hy_load6(ZHY, c0n + 8 * cg, m0n + 4 * tq, Ln, n0);
;             const v4u* dp = (const v4u*)(UCT + (size_t)(c0n + yc) * MT + m0n);
; #pragma unroll
;             for (int k = 0; k < 4; ++k) ny[k] = dp[8 * k + yp]; } }
.LBB0_948:
	s_add_i32 s21, s22, s70
	s_cmpk_gt_i32 s21, 0x11ff
	s_cselect_b64 s[8:9], -1, 0
	s_and_b64 vcc, exec, s[8:9]
	s_waitcnt vmcnt(4)
	ds_write2_b64 v103, v[20:21], v[22:23] offset1:1
	ds_write2_b64 v103, v[16:17], v[18:19] offset0:16 offset1:17
	ds_write2_b64 v103, v[12:13], v[14:15] offset0:32 offset1:33
	ds_write2_b64 v103, v[8:9], v[10:11] offset0:48 offset1:49
	s_cbranch_vccnz .LBB0_947
	s_mul_hi_i32 s10, s21, 0x2aaaaaab
	s_lshr_b32 s11, s10, 31
	s_ashr_i32 s10, s10, 1
	s_add_i32 s11, s10, s11
	s_lshl_b32 s10, s11, 8
	s_mulk_i32 s11, 0xfd00
	s_add_i32 s11, s11, s17
	s_cmpk_lt_i32 s21, 0xc00
	v_add_u32_e32 v10, s10, v99
	s_cselect_b32 s23, s19, 0xfff
	v_add_u32_e32 v0, s11, v100
	v_and_b32_e32 v1, s23, v10
	v_cmp_ne_u32_e32 vcc, 0, v1
	v_ashrrev_i32_e32 v1, 31, v0
	v_mov_b32_e32 v2, v97
	v_mov_b32_e32 v3, v97
	v_lshl_add_u64 v[8:9], v[0:1], 1, s[2:3]
	v_mov_b32_e32 v0, 0
	v_mov_b32_e32 v1, v97
	v_mov_b64_e32 v[6:7], v[2:3]
	v_mov_b64_e32 v[4:5], v[0:1]
	s_and_saveexec_b64 s[12:13], vcc
	s_cbranch_execz .LBB0_951
	v_add_u32_e32 v4, -1, v10
	v_mad_i64_i32 v[4:5], s[24:25], v4, s14, v[8:9]
	global_load_dwordx4 v[4:7], v[4:5], off
